# v2 + first two K-loop waits after an FFN-up epilogue relaxed to vmcnt(16) + P0 x->bf16 loop 4x unrolled
# baseline (speedup 1.0000x reference)
.LBB0_84:
	v_mov_b64_e32 v[4:5], 0x7fffff
	v_cmp_gt_u64_e32 vcc, s[8:9], v[4:5]
	s_mov_b64 s[0:1], 0x7fffff
	v_lshlrev_b32_e32 v6, 5, v68
	v_lshlrev_b32_e32 v4, 4, v68
	s_cbranch_vccnz .LBB0_88
	v_readlane_b32 s10, v255, 13
	v_readlane_b32 s11, v255, 14
	s_lshl_b64 s[2:3], s[10:11], 11
	s_add_u32 s2, s16, s2
	v_mov_b32_e32 v7, 0
	s_addc_u32 s3, s17, s3
	v_lshl_add_u64 v[8:9], s[2:3], 0, v[6:7]
	s_lshl_b64 s[2:3], s[82:83], 11
	s_lshl_b64 s[10:11], s[10:11], 10
	s_add_u32 s10, s70, s10
	v_mov_b32_e32 v5, v7
	s_addc_u32 s11, s71, s11
	v_lshl_add_u64 v[10:11], s[10:11], 0, v[4:5]
	s_mov_b64 s[10:11], 0x5400000
	v_lshl_add_u64 v[8:9], v[8:9], 0, 16
	v_lshl_add_u64 v[10:11], v[10:11], 0, s[10:11]
	s_lshl_b64 s[16:17], s[82:83], 10
	s_mov_b64 s[10:11], 0
	v_mov_b64_e32 v[12:13], v[2:3]
	s_lshl_b64 s[100:101], s[6:7], 2
.Lcvtm_c0:
	v_lshl_add_u64 v[80:81], v[12:13], 0, s[100:101]
	v_cmp_ge_u64_e32 vcc, s[0:1], v[80:81]
	s_cmp_eq_u64 vcc, exec
	s_cbranch_scc0 .LBB0_86
	global_load_dwordx4 v[40:43], v[8:9], off offset:-16 nt
	global_load_dwordx4 v[44:47], v[8:9], off nt
	v_lshl_add_u64 v[12:13], v[12:13], 0, s[6:7]
	v_lshl_add_u64 v[8:9], v[8:9], 0, s[2:3]
	global_load_dwordx4 v[48:51], v[8:9], off offset:-16 nt
	global_load_dwordx4 v[52:55], v[8:9], off nt
	v_lshl_add_u64 v[12:13], v[12:13], 0, s[6:7]
	v_lshl_add_u64 v[8:9], v[8:9], 0, s[2:3]
	global_load_dwordx4 v[56:59], v[8:9], off offset:-16 nt
	global_load_dwordx4 v[60:63], v[8:9], off nt
	v_lshl_add_u64 v[12:13], v[12:13], 0, s[6:7]
	v_lshl_add_u64 v[8:9], v[8:9], 0, s[2:3]
	global_load_dwordx4 v[64:67], v[8:9], off offset:-16 nt
	global_load_dwordx4 v[68:71], v[8:9], off nt
	v_lshl_add_u64 v[12:13], v[12:13], 0, s[6:7]
	v_lshl_add_u64 v[8:9], v[8:9], 0, s[2:3]
	s_waitcnt vmcnt(6)
	v_cvt_pk_bf16_f32 v40, v40, v41
	v_cvt_pk_bf16_f32 v41, v42, v43
	v_cvt_pk_bf16_f32 v42, v44, v45
	v_cvt_pk_bf16_f32 v43, v46, v47
	global_store_dwordx4 v[10:11], v[40:43], off
	v_lshl_add_u64 v[10:11], v[10:11], 0, s[16:17]
	s_waitcnt vmcnt(5)
	v_cvt_pk_bf16_f32 v48, v48, v49
	v_cvt_pk_bf16_f32 v49, v50, v51
	v_cvt_pk_bf16_f32 v50, v52, v53
	v_cvt_pk_bf16_f32 v51, v54, v55
	global_store_dwordx4 v[10:11], v[48:51], off
	v_lshl_add_u64 v[10:11], v[10:11], 0, s[16:17]
	s_waitcnt vmcnt(4)
	v_cvt_pk_bf16_f32 v56, v56, v57
	v_cvt_pk_bf16_f32 v57, v58, v59
	v_cvt_pk_bf16_f32 v58, v60, v61
	v_cvt_pk_bf16_f32 v59, v62, v63
	global_store_dwordx4 v[10:11], v[56:59], off
	v_lshl_add_u64 v[10:11], v[10:11], 0, s[16:17]
	s_waitcnt vmcnt(3)
	v_cvt_pk_bf16_f32 v64, v64, v65
	v_cvt_pk_bf16_f32 v65, v66, v67
	v_cvt_pk_bf16_f32 v66, v68, v69
	v_cvt_pk_bf16_f32 v67, v70, v71
	global_store_dwordx4 v[10:11], v[64:67], off
	v_lshl_add_u64 v[10:11], v[10:11], 0, s[16:17]
	s_branch .Lcvtm_c0
